# GEMM unit loops (in-proj, gate/up): next-unit decode moved one more load segment down the peeled K iteration
# speedup vs baseline: 1.0050x; 1.0050x over previous
.LBB0_255:
	s_cmp_eq_u32 s86, 14
	s_cbranch_scc1 .Lz255
	s_add_u32 s88, s8, 0x100
	s_addc_u32 s89, s9, 0
	s_add_u32 s8, s38, 0x40080
	s_addc_u32 s9, s39, 0
	s_mov_b32 s90, -2
	s_add_u32 s38, s8, 0xfffc0080
	s_addc_u32 s39, s9, -1
	s_add_i32 s91, 0, 0x10000
	s_cmp_eq_u32 s90, 12
	s_cselect_b32 s57, s31, s39
	s_cselect_b32 s56, s47, s38
	s_cselect_b32 s39, s29, s89
	s_cselect_b32 s38, s87, s88
	s_add_i32 s94, 0, 0x14000
	v_add_u32_e32 v140, s91, v183
	v_add_u32_e32 v168, s94, v183
	ds_read_b128 v[128:131], v140
	ds_read_b128 v[132:135], v140 offset:1024
	ds_read_b128 v[136:139], v140 offset:2048
	ds_read_b128 v[140:143], v140 offset:3072
	ds_read_b128 v[144:147], v168
	ds_read_b128 v[148:151], v168 offset:1024
	ds_read_b128 v[164:167], v168 offset:2048
	ds_read_b128 v[168:171], v168 offset:3072
	v_lshl_add_u64 v[184:185], s[8:9], 0, v[162:163]
	s_add_i32 m0, s55, 0xc000
	ds_read_b128 v[172:175], v187
	ds_read_b128 v[176:179], v187 offset:1024
	ds_read_b128 v[188:191], v187 offset:2048
	ds_read_b128 v[202:205], v187 offset:3072
	ds_read_b128 v[206:209], v187 offset:4096
	ds_read_b128 v[210:213], v187 offset:5120
	ds_read_b128 v[214:217], v187 offset:6144
	ds_read_b128 v[218:221], v187 offset:7168
	global_load_lds_dwordx4 v[184:185], off
	v_lshl_add_u64 v[184:185], s[8:9], 0, v[160:161]
	s_add_i32 m0, s55, 0xe000
	s_nop 0
	global_load_lds_dwordx4 v[184:185], off
	s_waitcnt vmcnt(8)
	s_waitcnt lgkmcnt(0)
	s_barrier
	s_setprio 1
	s_waitcnt lgkmcnt(0)
	v_mfma_f32_16x16x32_bf16 v[124:127], v[128:131], v[172:175], 0
	v_mfma_f32_16x16x32_bf16 v[120:123], v[136:139], v[172:175], 0
	v_mfma_f32_16x16x32_bf16 v[112:115], v[128:131], v[188:191], 0
	v_mfma_f32_16x16x32_bf16 v[104:107], v[136:139], v[188:191], 0
	v_mfma_f32_16x16x32_bf16 v[96:99], v[128:131], v[206:209], 0
	v_mfma_f32_16x16x32_bf16 v[88:91], v[136:139], v[206:209], 0
	v_mfma_f32_16x16x32_bf16 v[80:83], v[128:131], v[214:217], 0
	v_mfma_f32_16x16x32_bf16 v[72:75], v[136:139], v[214:217], 0
	v_mfma_f32_16x16x32_bf16 v[124:127], v[132:135], v[176:179], v[124:127]
	v_mfma_f32_16x16x32_bf16 v[120:123], v[140:143], v[176:179], v[120:123]
	v_mfma_f32_16x16x32_bf16 v[112:115], v[132:135], v[202:205], v[112:115]
	v_mfma_f32_16x16x32_bf16 v[104:107], v[140:143], v[202:205], v[104:107]
	v_mfma_f32_16x16x32_bf16 v[96:99], v[132:135], v[210:213], v[96:99]
	v_mfma_f32_16x16x32_bf16 v[88:91], v[140:143], v[210:213], v[88:91]
	v_mfma_f32_16x16x32_bf16 v[80:83], v[132:135], v[218:221], v[80:83]
	v_mfma_f32_16x16x32_bf16 v[72:75], v[140:143], v[218:221], v[72:75]
	s_setprio 0
	s_setprio 1
	v_mfma_f32_16x16x32_bf16 v[116:119], v[144:147], v[172:175], 0
	v_mfma_f32_16x16x32_bf16 v[108:111], v[164:167], v[172:175], 0
	v_mfma_f32_16x16x32_bf16 v[100:103], v[144:147], v[188:191], 0
	v_mfma_f32_16x16x32_bf16 v[92:95], v[164:167], v[188:191], 0
	v_mfma_f32_16x16x32_bf16 v[84:87], v[144:147], v[206:209], 0
	v_mfma_f32_16x16x32_bf16 v[76:79], v[164:167], v[206:209], 0
	v_mfma_f32_16x16x32_bf16 v[68:71], v[144:147], v[214:217], 0
	v_mfma_f32_16x16x32_bf16 v[64:67], v[164:167], v[214:217], 0
	v_mfma_f32_16x16x32_bf16 v[116:119], v[148:151], v[176:179], v[116:119]
	v_mfma_f32_16x16x32_bf16 v[108:111], v[168:171], v[176:179], v[108:111]
	v_mfma_f32_16x16x32_bf16 v[100:103], v[148:151], v[202:205], v[100:103]
	v_mfma_f32_16x16x32_bf16 v[92:95], v[168:171], v[202:205], v[92:95]
	v_mfma_f32_16x16x32_bf16 v[84:87], v[148:151], v[210:213], v[84:87]
	v_mfma_f32_16x16x32_bf16 v[76:79], v[168:171], v[210:213], v[76:79]
	v_mfma_f32_16x16x32_bf16 v[68:71], v[148:151], v[218:221], v[68:71]
	v_mfma_f32_16x16x32_bf16 v[64:67], v[168:171], v[218:221], v[64:67]
	s_setprio 0
	s_barrier
	s_add_i32 s91, s91, s54
	v_lshl_add_u64 v[184:185], s[38:39], 0, v[192:193]
	s_mov_b32 m0, s91
	ds_read_b128 v[172:175], v187 offset:16384
	ds_read_b128 v[176:179], v187 offset:17408
	ds_read_b128 v[188:191], v187 offset:18432
	ds_read_b128 v[202:205], v187 offset:19456
	ds_read_b128 v[206:209], v187 offset:20480
	ds_read_b128 v[210:213], v187 offset:21504
	ds_read_b128 v[214:217], v187 offset:22528
	ds_read_b128 v[218:221], v187 offset:23552
	global_load_lds_dwordx4 v[184:185], off
	s_add_i32 m0, s91, 0x2000
	s_add_u32 s92, s38, 0x40000
	v_lshl_add_u64 v[222:223], s[38:39], 0, v[152:153]
	s_addc_u32 s93, s39, 0
	s_add_i32 s91, s94, s54
	global_load_lds_dwordx4 v[222:223], off
	v_lshl_add_u64 v[224:225], s[92:93], 0, v[192:193]
	s_mov_b32 m0, s91
	v_lshl_add_u64 v[226:227], s[56:57], 0, v[154:155]
	global_load_lds_dwordx4 v[224:225], off
	v_lshl_add_u64 v[224:225], s[92:93], 0, v[152:153]
	s_add_i32 m0, s91, 0x2000
	s_nop 0
	global_load_lds_dwordx4 v[224:225], off
	v_lshl_add_u64 v[224:225], s[56:57], 0, v[156:157]
	s_mov_b32 m0, s55
	s_nop 0
	global_load_lds_dwordx4 v[224:225], off
	s_mov_b32 m0, s60
	s_nop 0
	global_load_lds_dwordx4 v[226:227], off
	s_add_i32 s85, s85, 1
	s_mul_i32 s6, s85, s43
	s_mul_hi_u32 s7, s85, s42
	s_add_i32 s7, s7, s6
	s_mul_i32 s6, s85, s42
	s_add_u32 s34, s6, s2
	s_addc_u32 s35, s7, s41
	v_mov_b64_e32 v[0:1], 0xf00
	v_cmp_lt_i64_e64 s[6:7], s[34:35], v[0:1]
	v_mov_b64_e32 v[0:1], 0xeff
	v_cmp_gt_i64_e32 vcc, s[34:35], v[0:1]
	s_cbranch_vccnz .LBB0_257
	s_ashr_i32 s28, s34, 31
	s_lshr_b32 s28, s28, 29
	s_add_i32 s28, s34, s28
	s_ashr_i32 s29, s28, 3
	s_and_b32 s28, s28, -8
	s_sub_i32 s28, s34, s28
	s_cmp_lt_i32 s28, 0
	s_movk_i32 s30, 0x1e1
	s_cselect_b32 s30, s30, 0x1e0
	s_mul_i32 s28, s28, s30
	s_add_i32 s28, s28, s29
	s_mul_hi_i32 s29, s28, 0x88888889
	s_add_i32 s29, s29, s28
	s_lshr_b32 s30, s29, 31
	s_ashr_i32 s29, s29, 6
	s_add_i32 s29, s29, s30
	s_lshl_b32 s30, s29, 3
	s_sub_i32 s31, 0x100, s30
	s_min_i32 s31, s31, 8
	s_abs_i32 s34, s31
	v_cvt_f32_u32_e32 v0, s34
	s_sub_i32 s36, 0, s34
	s_mulk_i32 s29, 0x78
	s_sub_i32 s29, s28, s29
	v_rcp_iflag_f32_e32 v0, v0
	s_abs_i32 s28, s29
	s_xor_b32 s35, s29, s31
	s_ashr_i32 s35, s35, 31
	v_mul_f32_e32 v0, 0x4f7ffffe, v0
	v_cvt_u32_f32_e32 v0, v0
	s_nop 0
	v_readfirstlane_b32 s37, v0
	s_mul_i32 s36, s36, s37
	s_mul_hi_u32 s36, s37, s36
	s_add_i32 s37, s37, s36
	s_mul_hi_u32 s36, s28, s37
	s_mul_i32 s37, s36, s34
	s_sub_i32 s28, s28, s37
	s_add_i32 s47, s36, 1
	s_sub_i32 s37, s28, s34
	s_cmp_ge_u32 s28, s34
	s_cselect_b32 s36, s47, s36
	s_cselect_b32 s28, s37, s28
	s_add_i32 s37, s36, 1
	s_cmp_ge_u32 s28, s34
	s_cselect_b32 s28, s37, s36
	s_xor_b32 s28, s28, s35
	s_sub_i32 s28, s28, s35
	s_mul_i32 s31, s28, s31
	s_sub_i32 s29, s29, s31
	s_add_i32 s30, s30, s29
.LBB0_257:
	s_ashr_i32 s31, s30, 31
	s_lshl_b64 s[34:35], s[30:31], 19
	s_add_u32 s34, s48, s34
	s_addc_u32 s35, s49, s35
	s_and_b64 s[36:37], s[6:7], exec
	s_cselect_b32 s31, s35, s57
	s_cselect_b32 s47, s34, s56
	s_ashr_i32 s29, s28, 31
	s_lshl_b64 s[36:37], s[28:29], 19
	s_add_u32 s36, s50, s36
	s_addc_u32 s37, s51, s37
	s_and_b64 s[100:101], s[6:7], exec
	s_cselect_b32 s29, s37, s89
	s_cselect_b32 s87, s36, s88
	s_waitcnt vmcnt(8)
	s_waitcnt lgkmcnt(0)
	s_barrier
	s_setprio 1
	s_waitcnt lgkmcnt(0)
	v_mfma_f32_16x16x32_bf16 v[60:63], v[128:131], v[172:175], 0
	v_mfma_f32_16x16x32_bf16 v[56:59], v[136:139], v[172:175], 0
	v_mfma_f32_16x16x32_bf16 v[48:51], v[128:131], v[188:191], 0
	v_mfma_f32_16x16x32_bf16 v[40:43], v[136:139], v[188:191], 0
	v_mfma_f32_16x16x32_bf16 v[32:35], v[128:131], v[206:209], 0
	v_mfma_f32_16x16x32_bf16 v[24:27], v[136:139], v[206:209], 0
	v_mfma_f32_16x16x32_bf16 v[16:19], v[128:131], v[214:217], 0
	v_mfma_f32_16x16x32_bf16 v[8:11], v[136:139], v[214:217], 0
	v_mfma_f32_16x16x32_bf16 v[60:63], v[132:135], v[176:179], v[60:63]
	v_mfma_f32_16x16x32_bf16 v[56:59], v[140:143], v[176:179], v[56:59]
	v_mfma_f32_16x16x32_bf16 v[48:51], v[132:135], v[202:205], v[48:51]
	v_mfma_f32_16x16x32_bf16 v[40:43], v[140:143], v[202:205], v[40:43]
	v_mfma_f32_16x16x32_bf16 v[32:35], v[132:135], v[210:213], v[32:35]
	v_mfma_f32_16x16x32_bf16 v[24:27], v[140:143], v[210:213], v[24:27]
	v_mfma_f32_16x16x32_bf16 v[16:19], v[132:135], v[218:221], v[16:19]
	v_mfma_f32_16x16x32_bf16 v[8:11], v[140:143], v[218:221], v[8:11]
	s_setprio 0
	s_setprio 1
	v_mfma_f32_16x16x32_bf16 v[52:55], v[144:147], v[172:175], 0
	v_mfma_f32_16x16x32_bf16 v[44:47], v[164:167], v[172:175], 0
	v_mfma_f32_16x16x32_bf16 v[36:39], v[144:147], v[188:191], 0
	v_mfma_f32_16x16x32_bf16 v[28:31], v[164:167], v[188:191], 0
	v_mfma_f32_16x16x32_bf16 v[20:23], v[144:147], v[206:209], 0
	v_mfma_f32_16x16x32_bf16 v[12:15], v[164:167], v[206:209], 0
	v_mfma_f32_16x16x32_bf16 v[4:7], v[144:147], v[214:217], 0
	v_mfma_f32_16x16x32_bf16 v[0:3], v[164:167], v[214:217], 0
	v_mfma_f32_16x16x32_bf16 v[52:55], v[148:151], v[176:179], v[52:55]
	v_mfma_f32_16x16x32_bf16 v[44:47], v[168:171], v[176:179], v[44:47]
	v_mfma_f32_16x16x32_bf16 v[36:39], v[148:151], v[202:205], v[36:39]
	v_mfma_f32_16x16x32_bf16 v[28:31], v[168:171], v[202:205], v[28:31]
	v_mfma_f32_16x16x32_bf16 v[20:23], v[148:151], v[210:213], v[20:23]
	v_mfma_f32_16x16x32_bf16 v[12:15], v[168:171], v[210:213], v[12:15]
	v_mfma_f32_16x16x32_bf16 v[4:7], v[148:151], v[218:221], v[4:7]
	v_mfma_f32_16x16x32_bf16 v[0:3], v[168:171], v[218:221], v[0:3]
	s_setprio 0
	s_barrier
	s_add_i32 s91, 0, 0x18000
	s_add_i32 s92, 0, 0x1c000
	v_add_u32_e32 v140, s91, v183
	v_add_u32_e32 v168, s92, v183
	ds_read_b128 v[128:131], v140
	ds_read_b128 v[132:135], v140 offset:1024
	ds_read_b128 v[136:139], v140 offset:2048
	ds_read_b128 v[140:143], v140 offset:3072
	ds_read_b128 v[144:147], v168
	ds_read_b128 v[148:151], v168 offset:1024
	ds_read_b128 v[164:167], v168 offset:2048
	ds_read_b128 v[168:171], v168 offset:3072
	s_add_u32 s56, s56, 0x40000
	s_addc_u32 s57, s57, 0
	s_mov_b32 m0, s61
	v_lshl_add_u64 v[228:229], s[56:57], 0, v[156:157]
	ds_read_b128 v[172:175], v187 offset:32768
	ds_read_b128 v[176:179], v187 offset:33792
	ds_read_b128 v[188:191], v187 offset:34816
	ds_read_b128 v[202:205], v187 offset:35840
	ds_read_b128 v[206:209], v187 offset:36864
	ds_read_b128 v[210:213], v187 offset:37888
	ds_read_b128 v[214:217], v187 offset:38912
	ds_read_b128 v[218:221], v187 offset:39936
	global_load_lds_dwordx4 v[228:229], off
	v_lshl_add_u64 v[228:229], s[56:57], 0, v[154:155]
	s_mov_b32 m0, s82
	s_nop 0
	global_load_lds_dwordx4 v[228:229], off
	s_waitcnt vmcnt(8)
	s_waitcnt lgkmcnt(0)
	s_barrier
	s_setprio 1
	s_waitcnt lgkmcnt(0)
	v_mfma_f32_16x16x32_bf16 v[124:127], v[128:131], v[172:175], v[124:127]
	v_mfma_f32_16x16x32_bf16 v[120:123], v[136:139], v[172:175], v[120:123]
	v_mfma_f32_16x16x32_bf16 v[112:115], v[128:131], v[188:191], v[112:115]
	v_mfma_f32_16x16x32_bf16 v[104:107], v[136:139], v[188:191], v[104:107]
	v_mfma_f32_16x16x32_bf16 v[96:99], v[128:131], v[206:209], v[96:99]
	v_mfma_f32_16x16x32_bf16 v[88:91], v[136:139], v[206:209], v[88:91]
	v_mfma_f32_16x16x32_bf16 v[80:83], v[128:131], v[214:217], v[80:83]
	v_mfma_f32_16x16x32_bf16 v[72:75], v[136:139], v[214:217], v[72:75]
	v_mfma_f32_16x16x32_bf16 v[124:127], v[132:135], v[176:179], v[124:127]
	v_mfma_f32_16x16x32_bf16 v[120:123], v[140:143], v[176:179], v[120:123]
	v_mfma_f32_16x16x32_bf16 v[112:115], v[132:135], v[202:205], v[112:115]
	v_mfma_f32_16x16x32_bf16 v[104:107], v[140:143], v[202:205], v[104:107]
	v_mfma_f32_16x16x32_bf16 v[96:99], v[132:135], v[210:213], v[96:99]
	v_mfma_f32_16x16x32_bf16 v[88:91], v[140:143], v[210:213], v[88:91]
	v_mfma_f32_16x16x32_bf16 v[80:83], v[132:135], v[218:221], v[80:83]
	v_mfma_f32_16x16x32_bf16 v[72:75], v[140:143], v[218:221], v[72:75]
	s_setprio 0
	s_setprio 1
	v_mfma_f32_16x16x32_bf16 v[116:119], v[144:147], v[172:175], v[116:119]
	v_mfma_f32_16x16x32_bf16 v[108:111], v[164:167], v[172:175], v[108:111]
	v_mfma_f32_16x16x32_bf16 v[100:103], v[144:147], v[188:191], v[100:103]
	v_mfma_f32_16x16x32_bf16 v[92:95], v[164:167], v[188:191], v[92:95]
	v_mfma_f32_16x16x32_bf16 v[84:87], v[144:147], v[206:209], v[84:87]
	v_mfma_f32_16x16x32_bf16 v[76:79], v[164:167], v[206:209], v[76:79]
	v_mfma_f32_16x16x32_bf16 v[68:71], v[144:147], v[214:217], v[68:71]
	v_mfma_f32_16x16x32_bf16 v[64:67], v[164:167], v[214:217], v[64:67]
	v_mfma_f32_16x16x32_bf16 v[116:119], v[148:151], v[176:179], v[116:119]
	v_mfma_f32_16x16x32_bf16 v[108:111], v[168:171], v[176:179], v[108:111]
	v_mfma_f32_16x16x32_bf16 v[100:103], v[148:151], v[202:205], v[100:103]
	v_mfma_f32_16x16x32_bf16 v[92:95], v[168:171], v[202:205], v[92:95]
	v_mfma_f32_16x16x32_bf16 v[84:87], v[148:151], v[210:213], v[84:87]
	v_mfma_f32_16x16x32_bf16 v[76:79], v[168:171], v[210:213], v[76:79]
	v_mfma_f32_16x16x32_bf16 v[68:71], v[148:151], v[218:221], v[68:71]
	v_mfma_f32_16x16x32_bf16 v[64:67], v[168:171], v[218:221], v[64:67]
	s_setprio 0
	s_barrier
	s_add_i32 s56, s91, s54
	v_lshl_add_u64 v[184:185], v[184:185], 0, s[76:77]
	s_mov_b32 m0, s56
	ds_read_b128 v[172:175], v187 offset:49152
	ds_read_b128 v[176:179], v187 offset:50176
	ds_read_b128 v[188:191], v187 offset:51200
	ds_read_b128 v[202:205], v187 offset:52224
	ds_read_b128 v[206:209], v187 offset:53248
	ds_read_b128 v[210:213], v187 offset:54272
	ds_read_b128 v[214:217], v187 offset:55296
	ds_read_b128 v[218:221], v187 offset:56320
	global_load_lds_dwordx4 v[184:185], off
	s_add_i32 m0, s56, 0x2000
	s_add_u32 s38, s38, 0x40080
	v_lshl_add_u64 v[184:185], v[222:223], 0, s[76:77]
	s_addc_u32 s39, s39, 0
	s_add_i32 s56, s92, s54
	global_load_lds_dwordx4 v[184:185], off
	v_lshl_add_u64 v[184:185], s[38:39], 0, v[192:193]
	s_mov_b32 m0, s56
	s_nop 0
	global_load_lds_dwordx4 v[184:185], off
	v_lshl_add_u64 v[184:185], s[38:39], 0, v[152:153]
	s_add_i32 m0, s56, 0x2000
	s_nop 0
	global_load_lds_dwordx4 v[184:185], off
	v_lshl_add_u64 v[184:185], v[224:225], 0, s[76:77]
	s_mov_b32 m0, s68
	s_nop 0
	global_load_lds_dwordx4 v[184:185], off
	v_lshl_add_u64 v[184:185], v[226:227], 0, s[76:77]
	s_mov_b32 m0, s83
	s_nop 0
	global_load_lds_dwordx4 v[184:185], off
	s_waitcnt vmcnt(8)
	s_waitcnt lgkmcnt(0)
	s_barrier
	s_setprio 1
	s_waitcnt lgkmcnt(0)
	v_mfma_f32_16x16x32_bf16 v[60:63], v[128:131], v[172:175], v[60:63]
	v_mfma_f32_16x16x32_bf16 v[56:59], v[136:139], v[172:175], v[56:59]
	v_mfma_f32_16x16x32_bf16 v[48:51], v[128:131], v[188:191], v[48:51]
	v_mfma_f32_16x16x32_bf16 v[40:43], v[136:139], v[188:191], v[40:43]
	v_mfma_f32_16x16x32_bf16 v[32:35], v[128:131], v[206:209], v[32:35]
	v_mfma_f32_16x16x32_bf16 v[24:27], v[136:139], v[206:209], v[24:27]
	v_mfma_f32_16x16x32_bf16 v[16:19], v[128:131], v[214:217], v[16:19]
	v_mfma_f32_16x16x32_bf16 v[8:11], v[136:139], v[214:217], v[8:11]
	v_mfma_f32_16x16x32_bf16 v[60:63], v[132:135], v[176:179], v[60:63]
	v_mfma_f32_16x16x32_bf16 v[56:59], v[140:143], v[176:179], v[56:59]
	v_mfma_f32_16x16x32_bf16 v[48:51], v[132:135], v[202:205], v[48:51]
	v_mfma_f32_16x16x32_bf16 v[40:43], v[140:143], v[202:205], v[40:43]
	v_mfma_f32_16x16x32_bf16 v[32:35], v[132:135], v[210:213], v[32:35]
	v_mfma_f32_16x16x32_bf16 v[24:27], v[140:143], v[210:213], v[24:27]
	v_mfma_f32_16x16x32_bf16 v[16:19], v[132:135], v[218:221], v[16:19]
	v_mfma_f32_16x16x32_bf16 v[8:11], v[140:143], v[218:221], v[8:11]
	s_setprio 0
	s_setprio 1
	v_mfma_f32_16x16x32_bf16 v[52:55], v[144:147], v[172:175], v[52:55]
	v_mfma_f32_16x16x32_bf16 v[44:47], v[164:167], v[172:175], v[44:47]
	v_mfma_f32_16x16x32_bf16 v[36:39], v[144:147], v[188:191], v[36:39]
	v_mfma_f32_16x16x32_bf16 v[28:31], v[164:167], v[188:191], v[28:31]
	v_mfma_f32_16x16x32_bf16 v[20:23], v[144:147], v[206:209], v[20:23]
	v_mfma_f32_16x16x32_bf16 v[12:15], v[164:167], v[206:209], v[12:15]
	v_mfma_f32_16x16x32_bf16 v[4:7], v[144:147], v[214:217], v[4:7]
	v_mfma_f32_16x16x32_bf16 v[0:3], v[164:167], v[214:217], v[0:3]
	v_mfma_f32_16x16x32_bf16 v[52:55], v[148:151], v[176:179], v[52:55]
	v_mfma_f32_16x16x32_bf16 v[44:47], v[168:171], v[176:179], v[44:47]
	v_mfma_f32_16x16x32_bf16 v[36:39], v[148:151], v[202:205], v[36:39]
	v_mfma_f32_16x16x32_bf16 v[28:31], v[168:171], v[202:205], v[28:31]
	v_mfma_f32_16x16x32_bf16 v[20:23], v[148:151], v[210:213], v[20:23]
	v_mfma_f32_16x16x32_bf16 v[12:15], v[168:171], v[210:213], v[12:15]
	v_mfma_f32_16x16x32_bf16 v[4:7], v[148:151], v[218:221], v[4:7]
	v_mfma_f32_16x16x32_bf16 v[0:3], v[168:171], v[218:221], v[0:3]
	s_setprio 0
	s_barrier
	s_add_i32 s90, s90, 2
	s_add_u32 s88, s88, 0x100
	s_addc_u32 s89, s89, 0
	s_add_u32 s8, s8, 0x100
	s_addc_u32 s9, s9, 0
	s_cmp_gt_u32 s90, 13

.LBB0_932:
	s_mov_b64 s[86:87], s[26:27]
	s_mov_b64 s[88:89], s[8:9]
	s_add_u32 s56, s8, 0x100
	s_addc_u32 s57, s9, 0
	s_add_u32 s8, s26, 0x40080
	s_addc_u32 s9, s27, 0
	s_mov_b32 s60, -2
	s_add_u32 s26, s8, 0xfffc0080
	s_addc_u32 s27, s9, -1
	s_add_i32 s61, 0, 0x10000
	s_cmp_eq_u32 s60, 12
	s_cselect_b32 s29, s21, s27
	s_cselect_b32 s28, s54, s26
	s_cselect_b32 s27, s19, s57
	s_cselect_b32 s26, s55, s56
	s_add_i32 s68, 0, 0x14000
	v_add_u32_e32 v140, s61, v185
	v_add_u32_e32 v168, s68, v185
	ds_read_b128 v[128:131], v140
	ds_read_b128 v[132:135], v140 offset:1024
	ds_read_b128 v[136:139], v140 offset:2048
	ds_read_b128 v[140:143], v140 offset:3072
	ds_read_b128 v[144:147], v168
	ds_read_b128 v[148:151], v168 offset:1024
	ds_read_b128 v[164:167], v168 offset:2048
	ds_read_b128 v[168:171], v168 offset:3072
	v_lshl_add_u64 v[180:181], s[8:9], 0, v[162:163]
	s_add_i32 m0, s37, 0xc000
	ds_read_b128 v[172:175], v189
	ds_read_b128 v[176:179], v189 offset:1024
	ds_read_b128 v[202:205], v189 offset:2048
	ds_read_b128 v[206:209], v189 offset:3072
	ds_read_b128 v[210:213], v189 offset:4096
	ds_read_b128 v[214:217], v189 offset:5120
	ds_read_b128 v[218:221], v189 offset:6144
	ds_read_b128 v[222:225], v189 offset:7168
	global_load_lds_dwordx4 v[180:181], off
	v_lshl_add_u64 v[180:181], s[8:9], 0, v[160:161]
	s_add_i32 m0, s37, 0xe000
	s_nop 0
	global_load_lds_dwordx4 v[180:181], off
	s_waitcnt vmcnt(8)
	s_waitcnt lgkmcnt(0)
	s_barrier
	s_setprio 1
	s_waitcnt lgkmcnt(0)
	v_mfma_f32_16x16x32_bf16 v[124:127], v[128:131], v[172:175], 0
	v_mfma_f32_16x16x32_bf16 v[116:119], v[136:139], v[172:175], 0
	v_mfma_f32_16x16x32_bf16 v[108:111], v[128:131], v[202:205], 0
	v_mfma_f32_16x16x32_bf16 v[100:103], v[136:139], v[202:205], 0
	v_mfma_f32_16x16x32_bf16 v[92:95], v[128:131], v[210:213], 0
	v_mfma_f32_16x16x32_bf16 v[84:87], v[136:139], v[210:213], 0
	v_mfma_f32_16x16x32_bf16 v[76:79], v[128:131], v[218:221], 0
	v_mfma_f32_16x16x32_bf16 v[68:71], v[136:139], v[218:221], 0
	v_mfma_f32_16x16x32_bf16 v[124:127], v[132:135], v[176:179], v[124:127]
	v_mfma_f32_16x16x32_bf16 v[116:119], v[140:143], v[176:179], v[116:119]
	v_mfma_f32_16x16x32_bf16 v[108:111], v[132:135], v[206:209], v[108:111]
	v_mfma_f32_16x16x32_bf16 v[100:103], v[140:143], v[206:209], v[100:103]
	v_mfma_f32_16x16x32_bf16 v[92:95], v[132:135], v[214:217], v[92:95]
	v_mfma_f32_16x16x32_bf16 v[84:87], v[140:143], v[214:217], v[84:87]
	v_mfma_f32_16x16x32_bf16 v[76:79], v[132:135], v[222:225], v[76:79]
	v_mfma_f32_16x16x32_bf16 v[68:71], v[140:143], v[222:225], v[68:71]
	s_setprio 0
	s_setprio 1
	v_mfma_f32_16x16x32_bf16 v[120:123], v[144:147], v[172:175], 0
	v_mfma_f32_16x16x32_bf16 v[112:115], v[164:167], v[172:175], 0
	v_mfma_f32_16x16x32_bf16 v[104:107], v[144:147], v[202:205], 0
	v_mfma_f32_16x16x32_bf16 v[96:99], v[164:167], v[202:205], 0
	v_mfma_f32_16x16x32_bf16 v[88:91], v[144:147], v[210:213], 0
	v_mfma_f32_16x16x32_bf16 v[80:83], v[164:167], v[210:213], 0
	v_mfma_f32_16x16x32_bf16 v[72:75], v[144:147], v[218:221], 0
	v_mfma_f32_16x16x32_bf16 v[64:67], v[164:167], v[218:221], 0
	v_mfma_f32_16x16x32_bf16 v[120:123], v[148:151], v[176:179], v[120:123]
	v_mfma_f32_16x16x32_bf16 v[112:115], v[168:171], v[176:179], v[112:115]
	v_mfma_f32_16x16x32_bf16 v[104:107], v[148:151], v[206:209], v[104:107]
	v_mfma_f32_16x16x32_bf16 v[96:99], v[168:171], v[206:209], v[96:99]
	v_mfma_f32_16x16x32_bf16 v[88:91], v[148:151], v[214:217], v[88:91]
	v_mfma_f32_16x16x32_bf16 v[80:83], v[168:171], v[214:217], v[80:83]
	v_mfma_f32_16x16x32_bf16 v[72:75], v[148:151], v[222:225], v[72:75]
	v_mfma_f32_16x16x32_bf16 v[64:67], v[168:171], v[222:225], v[64:67]
	s_setprio 0
	s_barrier
	s_add_i32 s61, s61, s36
	v_lshl_add_u64 v[180:181], s[26:27], 0, v[192:193]
	s_mov_b32 m0, s61
	ds_read_b128 v[172:175], v189 offset:16384
	ds_read_b128 v[176:179], v189 offset:17408
	ds_read_b128 v[202:205], v189 offset:18432
	ds_read_b128 v[206:209], v189 offset:19456
	ds_read_b128 v[210:213], v189 offset:20480
	ds_read_b128 v[214:217], v189 offset:21504
	ds_read_b128 v[218:221], v189 offset:22528
	ds_read_b128 v[222:225], v189 offset:23552
	global_load_lds_dwordx4 v[180:181], off
	s_add_i32 m0, s61, 0x2000
	s_add_u32 s82, s26, 0x40000
	v_lshl_add_u64 v[186:187], s[26:27], 0, v[152:153]
	s_addc_u32 s83, s27, 0
	s_add_i32 s61, s68, s36
	global_load_lds_dwordx4 v[186:187], off
	v_lshl_add_u64 v[190:191], s[82:83], 0, v[192:193]
	s_mov_b32 m0, s61
	v_lshl_add_u64 v[226:227], s[28:29], 0, v[154:155]
	global_load_lds_dwordx4 v[190:191], off
	v_lshl_add_u64 v[190:191], s[82:83], 0, v[152:153]
	s_add_i32 m0, s61, 0x2000
	s_nop 0
	global_load_lds_dwordx4 v[190:191], off
	v_lshl_add_u64 v[190:191], s[28:29], 0, v[156:157]
	s_mov_b32 m0, s37
	s_nop 0
	global_load_lds_dwordx4 v[190:191], off
	s_mov_b32 m0, s38
	s_nop 0
	global_load_lds_dwordx4 v[226:227], off
	s_add_i32 s49, s49, 1
	s_mul_i32 s6, s49, s43
	s_mul_hi_u32 s7, s49, s42
	s_add_i32 s7, s7, s6
	s_mul_i32 s6, s49, s42
	s_add_u32 s22, s6, s2
	s_addc_u32 s23, s7, s41
	v_cmp_gt_i64_e32 vcc, s[22:23], v[200:201]
	v_cmp_lt_i64_e64 s[6:7], s[22:23], v[198:199]
	s_cbranch_vccnz .LBB0_934
	s_ashr_i32 s18, s22, 31
	s_lshr_b32 s18, s18, 29
	s_add_i32 s18, s22, s18
	s_ashr_i32 s19, s18, 3
	s_and_b32 s18, s18, -8
	s_sub_i32 s18, s22, s18
	s_cmp_lt_i32 s18, 0
	s_movk_i32 s20, 0x2c1
	s_cselect_b32 s20, s20, 0x2c0
	s_mul_i32 s18, s18, s20
	s_add_i32 s18, s18, s19
	s_mul_hi_i32 s19, s18, 0x2e8ba2e9
	s_lshr_b32 s20, s19, 31
	s_ashr_i32 s19, s19, 5
	s_add_i32 s19, s19, s20
	s_lshl_b32 s20, s19, 3
	s_sub_i32 s21, 0x100, s20
	s_min_i32 s21, s21, 8
	s_abs_i32 s22, s21
	v_cvt_f32_u32_e32 v0, s22
	s_sub_i32 s24, 0, s22
	s_mulk_i32 s19, 0xb0
	s_sub_i32 s19, s18, s19
	v_rcp_iflag_f32_e32 v0, v0
	s_abs_i32 s18, s19
	s_xor_b32 s23, s19, s21
	s_ashr_i32 s23, s23, 31
	v_mul_f32_e32 v0, 0x4f7ffffe, v0
	v_cvt_u32_f32_e32 v0, v0
	s_nop 0
	v_readfirstlane_b32 s25, v0
	s_mul_i32 s24, s24, s25
	s_mul_hi_u32 s24, s25, s24
	s_add_i32 s25, s25, s24
	s_mul_hi_u32 s24, s18, s25
	s_mul_i32 s25, s24, s22
	s_sub_i32 s18, s18, s25
	s_add_i32 s32, s24, 1
	s_sub_i32 s25, s18, s22
	s_cmp_ge_u32 s18, s22
	s_cselect_b32 s24, s32, s24
	s_cselect_b32 s18, s25, s18
	s_add_i32 s25, s24, 1
	s_cmp_ge_u32 s18, s22
	s_cselect_b32 s18, s25, s24
	s_xor_b32 s18, s18, s23
	s_sub_i32 s18, s18, s23
	s_mul_i32 s21, s18, s21
	s_sub_i32 s19, s19, s21
	s_add_i32 s20, s20, s19
.LBB0_934:
	s_ashr_i32 s21, s20, 31
	s_lshl_b64 s[22:23], s[20:21], 19
	s_add_u32 s22, s30, s22
	s_addc_u32 s23, s31, s23
	s_and_b64 s[24:25], s[6:7], exec
	s_cselect_b32 s21, s23, s87
	s_cselect_b32 s54, s22, s86
	s_ashr_i32 s19, s18, 31
	s_lshl_b64 s[24:25], s[18:19], 19
	s_add_u32 s24, s34, s24
	s_addc_u32 s25, s35, s25
	s_and_b64 s[100:101], s[6:7], exec
	s_cselect_b32 s19, s25, s89
	s_cselect_b32 s55, s24, s88
	s_waitcnt vmcnt(8)
	s_waitcnt lgkmcnt(0)
	s_barrier
	s_setprio 1
	s_waitcnt lgkmcnt(0)
	v_mfma_f32_16x16x32_bf16 v[60:63], v[128:131], v[172:175], 0
	v_mfma_f32_16x16x32_bf16 v[52:55], v[136:139], v[172:175], 0
	v_mfma_f32_16x16x32_bf16 v[44:47], v[128:131], v[202:205], 0
	v_mfma_f32_16x16x32_bf16 v[36:39], v[136:139], v[202:205], 0
	v_mfma_f32_16x16x32_bf16 v[28:31], v[128:131], v[210:213], 0
	v_mfma_f32_16x16x32_bf16 v[20:23], v[136:139], v[210:213], 0
	v_mfma_f32_16x16x32_bf16 v[12:15], v[128:131], v[218:221], 0
	v_mfma_f32_16x16x32_bf16 v[4:7], v[136:139], v[218:221], 0
	v_mfma_f32_16x16x32_bf16 v[60:63], v[132:135], v[176:179], v[60:63]
	v_mfma_f32_16x16x32_bf16 v[52:55], v[140:143], v[176:179], v[52:55]
	v_mfma_f32_16x16x32_bf16 v[44:47], v[132:135], v[206:209], v[44:47]
	v_mfma_f32_16x16x32_bf16 v[36:39], v[140:143], v[206:209], v[36:39]
	v_mfma_f32_16x16x32_bf16 v[28:31], v[132:135], v[214:217], v[28:31]
	v_mfma_f32_16x16x32_bf16 v[20:23], v[140:143], v[214:217], v[20:23]
	v_mfma_f32_16x16x32_bf16 v[12:15], v[132:135], v[222:225], v[12:15]
	v_mfma_f32_16x16x32_bf16 v[4:7], v[140:143], v[222:225], v[4:7]
	s_setprio 0
	s_setprio 1
	v_mfma_f32_16x16x32_bf16 v[56:59], v[144:147], v[172:175], 0
	v_mfma_f32_16x16x32_bf16 v[48:51], v[164:167], v[172:175], 0
	v_mfma_f32_16x16x32_bf16 v[40:43], v[144:147], v[202:205], 0
	v_mfma_f32_16x16x32_bf16 v[32:35], v[164:167], v[202:205], 0
	v_mfma_f32_16x16x32_bf16 v[24:27], v[144:147], v[210:213], 0
	v_mfma_f32_16x16x32_bf16 v[16:19], v[164:167], v[210:213], 0
	v_mfma_f32_16x16x32_bf16 v[8:11], v[144:147], v[218:221], 0
	v_mfma_f32_16x16x32_bf16 v[0:3], v[164:167], v[218:221], 0
	v_mfma_f32_16x16x32_bf16 v[56:59], v[148:151], v[176:179], v[56:59]
	v_mfma_f32_16x16x32_bf16 v[48:51], v[168:171], v[176:179], v[48:51]
	v_mfma_f32_16x16x32_bf16 v[40:43], v[148:151], v[206:209], v[40:43]
	v_mfma_f32_16x16x32_bf16 v[32:35], v[168:171], v[206:209], v[32:35]
	v_mfma_f32_16x16x32_bf16 v[24:27], v[148:151], v[214:217], v[24:27]
	v_mfma_f32_16x16x32_bf16 v[16:19], v[168:171], v[214:217], v[16:19]
	v_mfma_f32_16x16x32_bf16 v[8:11], v[148:151], v[222:225], v[8:11]
	v_mfma_f32_16x16x32_bf16 v[0:3], v[168:171], v[222:225], v[0:3]
	s_setprio 0
	s_barrier
	s_add_i32 s61, 0, 0x18000
	s_add_i32 s68, 0, 0x1c000
	v_add_u32_e32 v140, s61, v185
	v_add_u32_e32 v168, s68, v185
	ds_read_b128 v[128:131], v140
	ds_read_b128 v[132:135], v140 offset:1024
	ds_read_b128 v[136:139], v140 offset:2048
	ds_read_b128 v[140:143], v140 offset:3072
	ds_read_b128 v[144:147], v168
	ds_read_b128 v[148:151], v168 offset:1024
	ds_read_b128 v[164:167], v168 offset:2048
	ds_read_b128 v[168:171], v168 offset:3072
	s_add_u32 s28, s28, 0x40000
	s_addc_u32 s29, s29, 0
	s_mov_b32 m0, s39
	v_lshl_add_u64 v[228:229], s[28:29], 0, v[156:157]
	ds_read_b128 v[172:175], v189 offset:32768
	ds_read_b128 v[176:179], v189 offset:33792
	ds_read_b128 v[202:205], v189 offset:34816
	ds_read_b128 v[206:209], v189 offset:35840
	ds_read_b128 v[210:213], v189 offset:36864
	ds_read_b128 v[214:217], v189 offset:37888
	ds_read_b128 v[218:221], v189 offset:38912
	ds_read_b128 v[222:225], v189 offset:39936
	global_load_lds_dwordx4 v[228:229], off
	v_lshl_add_u64 v[228:229], s[28:29], 0, v[154:155]
	s_mov_b32 m0, s46
	s_nop 0
	global_load_lds_dwordx4 v[228:229], off
	s_waitcnt vmcnt(8)
	s_waitcnt lgkmcnt(0)
	s_barrier
	s_setprio 1
	s_waitcnt lgkmcnt(0)
	v_mfma_f32_16x16x32_bf16 v[124:127], v[128:131], v[172:175], v[124:127]
	v_mfma_f32_16x16x32_bf16 v[116:119], v[136:139], v[172:175], v[116:119]
	v_mfma_f32_16x16x32_bf16 v[108:111], v[128:131], v[202:205], v[108:111]
	v_mfma_f32_16x16x32_bf16 v[100:103], v[136:139], v[202:205], v[100:103]
	v_mfma_f32_16x16x32_bf16 v[92:95], v[128:131], v[210:213], v[92:95]
	v_mfma_f32_16x16x32_bf16 v[84:87], v[136:139], v[210:213], v[84:87]
	v_mfma_f32_16x16x32_bf16 v[76:79], v[128:131], v[218:221], v[76:79]
	v_mfma_f32_16x16x32_bf16 v[68:71], v[136:139], v[218:221], v[68:71]
	v_mfma_f32_16x16x32_bf16 v[124:127], v[132:135], v[176:179], v[124:127]
	v_mfma_f32_16x16x32_bf16 v[116:119], v[140:143], v[176:179], v[116:119]
	v_mfma_f32_16x16x32_bf16 v[108:111], v[132:135], v[206:209], v[108:111]
	v_mfma_f32_16x16x32_bf16 v[100:103], v[140:143], v[206:209], v[100:103]
	v_mfma_f32_16x16x32_bf16 v[92:95], v[132:135], v[214:217], v[92:95]
	v_mfma_f32_16x16x32_bf16 v[84:87], v[140:143], v[214:217], v[84:87]
	v_mfma_f32_16x16x32_bf16 v[76:79], v[132:135], v[222:225], v[76:79]
	v_mfma_f32_16x16x32_bf16 v[68:71], v[140:143], v[222:225], v[68:71]
	s_setprio 0
	s_setprio 1
	v_mfma_f32_16x16x32_bf16 v[120:123], v[144:147], v[172:175], v[120:123]
	v_mfma_f32_16x16x32_bf16 v[112:115], v[164:167], v[172:175], v[112:115]
	v_mfma_f32_16x16x32_bf16 v[104:107], v[144:147], v[202:205], v[104:107]
	v_mfma_f32_16x16x32_bf16 v[96:99], v[164:167], v[202:205], v[96:99]
	v_mfma_f32_16x16x32_bf16 v[88:91], v[144:147], v[210:213], v[88:91]
	v_mfma_f32_16x16x32_bf16 v[80:83], v[164:167], v[210:213], v[80:83]
	v_mfma_f32_16x16x32_bf16 v[72:75], v[144:147], v[218:221], v[72:75]
	v_mfma_f32_16x16x32_bf16 v[64:67], v[164:167], v[218:221], v[64:67]
	v_mfma_f32_16x16x32_bf16 v[120:123], v[148:151], v[176:179], v[120:123]
	v_mfma_f32_16x16x32_bf16 v[112:115], v[168:171], v[176:179], v[112:115]
	v_mfma_f32_16x16x32_bf16 v[104:107], v[148:151], v[206:209], v[104:107]
	v_mfma_f32_16x16x32_bf16 v[96:99], v[168:171], v[206:209], v[96:99]
	v_mfma_f32_16x16x32_bf16 v[88:91], v[148:151], v[214:217], v[88:91]
	v_mfma_f32_16x16x32_bf16 v[80:83], v[168:171], v[214:217], v[80:83]
	v_mfma_f32_16x16x32_bf16 v[72:75], v[148:151], v[222:225], v[72:75]
	v_mfma_f32_16x16x32_bf16 v[64:67], v[168:171], v[222:225], v[64:67]
	s_setprio 0
	s_barrier
	s_add_i32 s28, s61, s36
	v_lshl_add_u64 v[180:181], v[180:181], 0, s[76:77]
	s_mov_b32 m0, s28
	ds_read_b128 v[172:175], v189 offset:49152
	ds_read_b128 v[176:179], v189 offset:50176
	ds_read_b128 v[202:205], v189 offset:51200
	ds_read_b128 v[206:209], v189 offset:52224
	ds_read_b128 v[210:213], v189 offset:53248
	ds_read_b128 v[214:217], v189 offset:54272
	ds_read_b128 v[218:221], v189 offset:55296
	ds_read_b128 v[222:225], v189 offset:56320
	global_load_lds_dwordx4 v[180:181], off
	s_add_i32 m0, s28, 0x2000
	s_add_u32 s26, s26, 0x40080
	v_lshl_add_u64 v[180:181], v[186:187], 0, s[76:77]
	s_addc_u32 s27, s27, 0
	s_add_i32 s28, s68, s36
	global_load_lds_dwordx4 v[180:181], off
	v_lshl_add_u64 v[180:181], s[26:27], 0, v[192:193]
	s_mov_b32 m0, s28
	s_nop 0
	global_load_lds_dwordx4 v[180:181], off
	v_lshl_add_u64 v[180:181], s[26:27], 0, v[152:153]
	s_add_i32 m0, s28, 0x2000
	s_nop 0
	global_load_lds_dwordx4 v[180:181], off
	v_lshl_add_u64 v[180:181], v[190:191], 0, s[76:77]
	s_mov_b32 m0, s47
	s_nop 0
	global_load_lds_dwordx4 v[180:181], off
	v_lshl_add_u64 v[180:181], v[226:227], 0, s[76:77]
	s_mov_b32 m0, s48
	s_nop 0
	global_load_lds_dwordx4 v[180:181], off
	s_waitcnt vmcnt(8)
	s_waitcnt lgkmcnt(0)
	s_barrier
	s_setprio 1
	s_waitcnt lgkmcnt(0)
	v_mfma_f32_16x16x32_bf16 v[60:63], v[128:131], v[172:175], v[60:63]
	v_mfma_f32_16x16x32_bf16 v[52:55], v[136:139], v[172:175], v[52:55]
	v_mfma_f32_16x16x32_bf16 v[44:47], v[128:131], v[202:205], v[44:47]
	v_mfma_f32_16x16x32_bf16 v[36:39], v[136:139], v[202:205], v[36:39]
	v_mfma_f32_16x16x32_bf16 v[28:31], v[128:131], v[210:213], v[28:31]
	v_mfma_f32_16x16x32_bf16 v[20:23], v[136:139], v[210:213], v[20:23]
	v_mfma_f32_16x16x32_bf16 v[12:15], v[128:131], v[218:221], v[12:15]
	v_mfma_f32_16x16x32_bf16 v[4:7], v[136:139], v[218:221], v[4:7]
	v_mfma_f32_16x16x32_bf16 v[60:63], v[132:135], v[176:179], v[60:63]
	v_mfma_f32_16x16x32_bf16 v[52:55], v[140:143], v[176:179], v[52:55]
	v_mfma_f32_16x16x32_bf16 v[44:47], v[132:135], v[206:209], v[44:47]
	v_mfma_f32_16x16x32_bf16 v[36:39], v[140:143], v[206:209], v[36:39]
	v_mfma_f32_16x16x32_bf16 v[28:31], v[132:135], v[214:217], v[28:31]
	v_mfma_f32_16x16x32_bf16 v[20:23], v[140:143], v[214:217], v[20:23]
	v_mfma_f32_16x16x32_bf16 v[12:15], v[132:135], v[222:225], v[12:15]
	v_mfma_f32_16x16x32_bf16 v[4:7], v[140:143], v[222:225], v[4:7]
	s_setprio 0
	s_setprio 1
	v_mfma_f32_16x16x32_bf16 v[56:59], v[144:147], v[172:175], v[56:59]
	v_mfma_f32_16x16x32_bf16 v[48:51], v[164:167], v[172:175], v[48:51]
	v_mfma_f32_16x16x32_bf16 v[40:43], v[144:147], v[202:205], v[40:43]
	v_mfma_f32_16x16x32_bf16 v[32:35], v[164:167], v[202:205], v[32:35]
	v_mfma_f32_16x16x32_bf16 v[24:27], v[144:147], v[210:213], v[24:27]
	v_mfma_f32_16x16x32_bf16 v[16:19], v[164:167], v[210:213], v[16:19]
	v_mfma_f32_16x16x32_bf16 v[8:11], v[144:147], v[218:221], v[8:11]
	v_mfma_f32_16x16x32_bf16 v[0:3], v[164:167], v[218:221], v[0:3]
	v_mfma_f32_16x16x32_bf16 v[56:59], v[148:151], v[176:179], v[56:59]
	v_mfma_f32_16x16x32_bf16 v[48:51], v[168:171], v[176:179], v[48:51]
	v_mfma_f32_16x16x32_bf16 v[40:43], v[148:151], v[206:209], v[40:43]
	v_mfma_f32_16x16x32_bf16 v[32:35], v[168:171], v[206:209], v[32:35]
	v_mfma_f32_16x16x32_bf16 v[24:27], v[148:151], v[214:217], v[24:27]
	v_mfma_f32_16x16x32_bf16 v[16:19], v[168:171], v[214:217], v[16:19]
	v_mfma_f32_16x16x32_bf16 v[8:11], v[148:151], v[222:225], v[8:11]
	v_mfma_f32_16x16x32_bf16 v[0:3], v[168:171], v[222:225], v[0:3]
	s_setprio 0
	s_barrier
	s_add_i32 s60, s60, 2
	s_add_u32 s56, s56, 0x100
	s_addc_u32 s57, s57, 0
	s_add_u32 s8, s8, 0x100
	s_addc_u32 s9, s9, 0
	s_cmp_gt_u32 s60, 13
